# P1 bias rows visited in a per-wave rotated order (six instruction streams), single wait for all loads
# speedup vs baseline: 1.0067x; 1.0005x over previous
; __device__ __forceinline__ void p1_rows(const Args& A, int lane, int wave) {
;     ...
;     for (int it = gw; it < DIN + NGU; it += NGW) {
;         const bool second = it >= DIN; const int dr = second ? it - DIN : it;
;         const bf16_t* wrow = (const bf16_t*)(ws + (second ? WS_W2GU : WS_WIN)) + (size_t)dr * DM;
;         const float* sh = mods + (second ? MOD_SH3 : MOD_SH2) * DM;
;         float a0 = 0.f, a1 = 0.f, a2 = 0.f, a3 = 0.f;
; #pragma unroll
;         for (int j = 0; j < 2; ++j) { const int k = 8 * lane + 512 * j; f32x4 wa, wb; pg8::unpack8(*(const u32x4*)(wrow + k), wa, wb);
;     ...
;             BDOT(a0, 0) BDOT(a1, 1) BDOT(a2, 2) BDOT(a3, 3)
.LBB0_143:
	s_cmpk_gt_i32 s6, 0x2fff
	s_cbranch_scc1 .LBB0_148
	s_waitcnt lgkmcnt(0)
	v_lshlrev_b32_e32 v11, 1, v34
	v_lshlrev_b32_e32 v32, 2, v34
	s_mov_b32 s14, 0x2d00000
	s_mov_b32 s15, 0x1a00000
	s_mov_b32 s0, s6
	s_add_i32 s9, s0, 0xffffe600
	s_cmpk_gt_i32 s0, 0x19ff
	s_cselect_b32 s9, s9, s0
	s_cselect_b32 s1, s14, s15
	s_lshl_b32 s9, s9, 11
	s_add_u32 s12, s4, s1
	s_addc_u32 s13, s5, 0
	s_add_u32 s12, s12, s9
	s_addc_u32 s13, s13, 0
	global_load_dwordx4 v[40:43], v11, s[12:13]
	global_load_dwordx4 v[44:47], v11, s[12:13] offset:1024
	s_add_i32 s0, s0, s8
	s_add_i32 s9, s0, 0xffffe600
	s_cmpk_gt_i32 s0, 0x19ff
	s_cselect_b32 s9, s9, s0
	s_cselect_b32 s1, s14, s15
	s_lshl_b32 s9, s9, 11
	s_add_u32 s12, s4, s1
	s_addc_u32 s13, s5, 0
	s_add_u32 s12, s12, s9
	s_addc_u32 s13, s13, 0
	global_load_dwordx4 v[48:51], v11, s[12:13]
	global_load_dwordx4 v[52:55], v11, s[12:13] offset:1024
	s_add_i32 s0, s0, s8
	s_add_i32 s9, s0, 0xffffe600
	s_cmpk_gt_i32 s0, 0x19ff
	s_cselect_b32 s9, s9, s0
	s_cselect_b32 s1, s14, s15
	s_lshl_b32 s9, s9, 11
	s_add_u32 s12, s4, s1
	s_addc_u32 s13, s5, 0
	s_add_u32 s12, s12, s9
	s_addc_u32 s13, s13, 0
	global_load_dwordx4 v[56:59], v11, s[12:13]
	global_load_dwordx4 v[60:63], v11, s[12:13] offset:1024
	s_add_i32 s0, s0, s8
	s_add_i32 s9, s0, 0xffffe600
	s_cmpk_gt_i32 s0, 0x19ff
	s_cselect_b32 s9, s9, s0
	s_cselect_b32 s1, s14, s15
	s_lshl_b32 s9, s9, 11
	s_add_u32 s12, s4, s1
	s_addc_u32 s13, s5, 0
	s_add_u32 s12, s12, s9
	s_addc_u32 s13, s13, 0
	global_load_dwordx4 v[64:67], v11, s[12:13]
	global_load_dwordx4 v[68:71], v11, s[12:13] offset:1024
	s_add_i32 s0, s0, s8
	s_add_i32 s9, s0, 0xffffe600
	s_cmpk_gt_i32 s0, 0x19ff
	s_cselect_b32 s9, s9, s0
	s_cselect_b32 s1, s14, s15
	s_lshl_b32 s9, s9, 11
	s_add_u32 s12, s4, s1
	s_addc_u32 s13, s5, 0
	s_add_u32 s12, s12, s9
	s_addc_u32 s13, s13, 0
	global_load_dwordx4 v[72:75], v11, s[12:13]
	global_load_dwordx4 v[76:79], v11, s[12:13] offset:1024
	s_add_i32 s0, s0, s8
	s_add_i32 s9, s0, 0xffffe600
	s_cmpk_gt_i32 s0, 0x19ff
	s_cselect_b32 s9, s9, s0
	s_cselect_b32 s1, s14, s15
	s_lshl_b32 s9, s9, 11
	s_add_u32 s12, s4, s1
	s_addc_u32 s13, s5, 0
	s_add_u32 s12, s12, s9
	s_addc_u32 s13, s13, 0
	global_load_dwordx4 v[80:83], v11, s[12:13]
	global_load_dwordx4 v[84:87], v11, s[12:13] offset:1024
	s_add_u32 s16, s4, 0x3000
	s_addc_u32 s17, s5, 0
	global_load_dwordx4 v[100:103], v32, s[16:17]
	global_load_dwordx4 v[104:107], v32, s[16:17] offset:16
	global_load_dwordx4 v[108:111], v32, s[16:17] offset:2048
	global_load_dwordx4 v[112:115], v32, s[16:17] offset:2064
	s_add_u32 s16, s16, 0x9000
	s_addc_u32 s17, s17, 0
	global_load_dwordx4 v[116:119], v32, s[16:17]
	global_load_dwordx4 v[120:123], v32, s[16:17] offset:16
	global_load_dwordx4 v[124:127], v32, s[16:17] offset:2048
	global_load_dwordx4 v[128:131], v32, s[16:17] offset:2064
	s_add_u32 s16, s16, 0x9000
	s_addc_u32 s17, s17, 0
	global_load_dwordx4 v[132:135], v32, s[16:17]
	global_load_dwordx4 v[136:139], v32, s[16:17] offset:16
	global_load_dwordx4 v[140:143], v32, s[16:17] offset:2048
	global_load_dwordx4 v[144:147], v32, s[16:17] offset:2064
	s_add_u32 s16, s16, 0x9000
	s_addc_u32 s17, s17, 0
	global_load_dwordx4 v[148:151], v32, s[16:17]
	global_load_dwordx4 v[152:155], v32, s[16:17] offset:16
	global_load_dwordx4 v[156:159], v32, s[16:17] offset:2048
	global_load_dwordx4 v[160:163], v32, s[16:17] offset:2064
	s_add_u32 s16, s4, 0x6000
	s_addc_u32 s17, s5, 0
	global_load_dwordx4 v[164:167], v32, s[16:17]
	global_load_dwordx4 v[168:171], v32, s[16:17] offset:16
	global_load_dwordx4 v[172:175], v32, s[16:17] offset:2048
	global_load_dwordx4 v[176:179], v32, s[16:17] offset:2064
	s_add_u32 s16, s16, 0x9000
	s_addc_u32 s17, s17, 0
	global_load_dwordx4 v[180:183], v32, s[16:17]
	global_load_dwordx4 v[184:187], v32, s[16:17] offset:16
	global_load_dwordx4 v[188:191], v32, s[16:17] offset:2048
	global_load_dwordx4 v[192:195], v32, s[16:17] offset:2064
	s_add_u32 s16, s16, 0x9000
	s_addc_u32 s17, s17, 0
	global_load_dwordx4 v[196:199], v32, s[16:17]
	global_load_dwordx4 v[200:203], v32, s[16:17] offset:16
	global_load_dwordx4 v[204:207], v32, s[16:17] offset:2048
	global_load_dwordx4 v[208:211], v32, s[16:17] offset:2064
	s_add_u32 s16, s16, 0x9000
	s_addc_u32 s17, s17, 0
	global_load_dwordx4 v[212:215], v32, s[16:17]
	global_load_dwordx4 v[216:219], v32, s[16:17] offset:16
	global_load_dwordx4 v[88:91], v32, s[16:17] offset:2048
	global_load_dwordx4 v[92:95], v32, s[16:17] offset:2064
	s_waitcnt vmcnt(0)
	s_and_b32 s21, s6, 7
	s_add_i32 s20, s21, -6
	s_cmp_ge_u32 s21, 6
	s_cselect_b32 s21, s20, s21
	s_mov_b32 s20, 6
	s_cmp_eq_u32 s21, 1
	s_cbranch_scc1 .Lp1b_row1
	s_cmp_eq_u32 s21, 2
	s_cbranch_scc1 .Lp1b_row2
	s_cmp_eq_u32 s21, 3
	s_cbranch_scc1 .Lp1b_row3
	s_cmp_eq_u32 s21, 4
	s_cbranch_scc1 .Lp1b_row4
	s_cmp_eq_u32 s21, 5
	s_cbranch_scc1 .Lp1b_row5
; __device__ __forceinline__ void p1_rows(const Args& A, int lane, int wave) {
;     ...
; #pragma unroll
;         for (int j = 0; j < 2; ++j) { const int k = 8 * lane + 512 * j; f32x4 wa, wb; pg8::unpack8(*(const u32x4*)(wrow + k), wa, wb);
;     ...
;             BDOT(a0, 0) BDOT(a1, 1) BDOT(a2, 2) BDOT(a3, 3)
;     ...
;         }
;         a0 = wave_sum(a0); a1 = wave_sum(a1); a2 = wave_sum(a2); a3 = wave_sum(a3);
.Lp1b_row0:
	v_lshlrev_b32_e32 v12, 16, v40
	v_and_b32_e32 v13, 0xffff0000, v40
	v_lshlrev_b32_e32 v14, 16, v41
	v_and_b32_e32 v15, 0xffff0000, v41
	v_lshlrev_b32_e32 v16, 16, v42
	v_and_b32_e32 v17, 0xffff0000, v42
	v_lshlrev_b32_e32 v18, 16, v43
	v_and_b32_e32 v19, 0xffff0000, v43
	v_lshlrev_b32_e32 v20, 16, v44
	v_and_b32_e32 v21, 0xffff0000, v44
	v_lshlrev_b32_e32 v22, 16, v45
	v_and_b32_e32 v23, 0xffff0000, v45
	v_lshlrev_b32_e32 v24, 16, v46
	v_and_b32_e32 v25, 0xffff0000, v46
	v_lshlrev_b32_e32 v26, 16, v47
	v_and_b32_e32 v27, 0xffff0000, v47
	v_mul_f32_e32 v228, v12, v100
	v_mul_f32_e32 v229, v12, v116
	v_mul_f32_e32 v230, v12, v132
	v_mul_f32_e32 v231, v12, v148
	v_fmac_f32_e32 v228, v13, v101
	v_fmac_f32_e32 v229, v13, v117
	v_fmac_f32_e32 v230, v13, v133
	v_fmac_f32_e32 v231, v13, v149
	v_fmac_f32_e32 v228, v14, v102
	v_fmac_f32_e32 v229, v14, v118
	v_fmac_f32_e32 v230, v14, v134
	v_fmac_f32_e32 v231, v14, v150
	v_fmac_f32_e32 v228, v15, v103
	v_fmac_f32_e32 v229, v15, v119
	v_fmac_f32_e32 v230, v15, v135
	v_fmac_f32_e32 v231, v15, v151
	v_fmac_f32_e32 v228, v16, v104
	v_fmac_f32_e32 v229, v16, v120
	v_fmac_f32_e32 v230, v16, v136
	v_fmac_f32_e32 v231, v16, v152
	v_fmac_f32_e32 v228, v17, v105
	v_fmac_f32_e32 v229, v17, v121
	v_fmac_f32_e32 v230, v17, v137
	v_fmac_f32_e32 v231, v17, v153
	v_fmac_f32_e32 v228, v18, v106
	v_fmac_f32_e32 v229, v18, v122
	v_fmac_f32_e32 v230, v18, v138
	v_fmac_f32_e32 v231, v18, v154
	v_fmac_f32_e32 v228, v19, v107
	v_fmac_f32_e32 v229, v19, v123
	v_fmac_f32_e32 v230, v19, v139
	v_fmac_f32_e32 v231, v19, v155
	v_fmac_f32_e32 v228, v20, v108
	v_fmac_f32_e32 v229, v20, v124
	v_fmac_f32_e32 v230, v20, v140
	v_fmac_f32_e32 v231, v20, v156
	v_fmac_f32_e32 v228, v21, v109
	v_fmac_f32_e32 v229, v21, v125
	v_fmac_f32_e32 v230, v21, v141
	v_fmac_f32_e32 v231, v21, v157
	v_fmac_f32_e32 v228, v22, v110
	v_fmac_f32_e32 v229, v22, v126
	v_fmac_f32_e32 v230, v22, v142
	v_fmac_f32_e32 v231, v22, v158
	v_fmac_f32_e32 v228, v23, v111
	v_fmac_f32_e32 v229, v23, v127
	v_fmac_f32_e32 v230, v23, v143
	v_fmac_f32_e32 v231, v23, v159
	v_fmac_f32_e32 v228, v24, v112
	v_fmac_f32_e32 v229, v24, v128
	v_fmac_f32_e32 v230, v24, v144
	v_fmac_f32_e32 v231, v24, v160
	v_fmac_f32_e32 v228, v25, v113
	v_fmac_f32_e32 v229, v25, v129
	v_fmac_f32_e32 v230, v25, v145
	v_fmac_f32_e32 v231, v25, v161
	v_fmac_f32_e32 v228, v26, v114
	v_fmac_f32_e32 v229, v26, v130
	v_fmac_f32_e32 v230, v26, v146
	v_fmac_f32_e32 v231, v26, v162
	v_fmac_f32_e32 v228, v27, v115
	v_fmac_f32_e32 v229, v27, v131
	v_fmac_f32_e32 v230, v27, v147
	v_fmac_f32_e32 v231, v27, v163
	v_add_f32_dpp v228, v228, v228 quad_perm:[1,0,3,2] row_mask:0xf bank_mask:0xf
	v_add_f32_dpp v229, v229, v229 quad_perm:[1,0,3,2] row_mask:0xf bank_mask:0xf
	v_add_f32_dpp v230, v230, v230 quad_perm:[1,0,3,2] row_mask:0xf bank_mask:0xf
	v_add_f32_dpp v231, v231, v231 quad_perm:[1,0,3,2] row_mask:0xf bank_mask:0xf
	v_add_f32_dpp v228, v228, v228 quad_perm:[2,3,0,1] row_mask:0xf bank_mask:0xf
	v_add_f32_dpp v229, v229, v229 quad_perm:[2,3,0,1] row_mask:0xf bank_mask:0xf
	v_add_f32_dpp v230, v230, v230 quad_perm:[2,3,0,1] row_mask:0xf bank_mask:0xf
	v_add_f32_dpp v231, v231, v231 quad_perm:[2,3,0,1] row_mask:0xf bank_mask:0xf
	v_add_f32_dpp v228, v228, v228 row_half_mirror row_mask:0xf bank_mask:0xf
	v_add_f32_dpp v229, v229, v229 row_half_mirror row_mask:0xf bank_mask:0xf
	v_add_f32_dpp v230, v230, v230 row_half_mirror row_mask:0xf bank_mask:0xf
	v_add_f32_dpp v231, v231, v231 row_half_mirror row_mask:0xf bank_mask:0xf
	v_add_f32_dpp v228, v228, v228 row_mirror row_mask:0xf bank_mask:0xf
	v_add_f32_dpp v229, v229, v229 row_mirror row_mask:0xf bank_mask:0xf
	v_add_f32_dpp v230, v230, v230 row_mirror row_mask:0xf bank_mask:0xf
	v_add_f32_dpp v231, v231, v231 row_mirror row_mask:0xf bank_mask:0xf
	v_add_f32_dpp v228, v228, v228 row_bcast:15 row_mask:0xa bank_mask:0xf
	v_add_f32_dpp v229, v229, v229 row_bcast:15 row_mask:0xa bank_mask:0xf
	v_add_f32_dpp v230, v230, v230 row_bcast:15 row_mask:0xa bank_mask:0xf
	v_add_f32_dpp v231, v231, v231 row_bcast:15 row_mask:0xa bank_mask:0xf
	v_add_f32_dpp v228, v228, v228 row_bcast:31 row_mask:0xc bank_mask:0xf
	v_add_f32_dpp v229, v229, v229 row_bcast:31 row_mask:0xc bank_mask:0xf
	v_add_f32_dpp v230, v230, v230 row_bcast:31 row_mask:0xc bank_mask:0xf
	v_add_f32_dpp v231, v231, v231 row_bcast:31 row_mask:0xc bank_mask:0xf
	s_add_i32 s20, s20, -1
	s_cmp_eq_u32 s20, 0
	s_cbranch_scc1 .Lp1b_done
; __device__ __forceinline__ void p1_rows(const Args& A, int lane, int wave) {
;     ...
; #pragma unroll
;         for (int j = 0; j < 2; ++j) { const int k = 8 * lane + 512 * j; f32x4 wa, wb; pg8::unpack8(*(const u32x4*)(wrow + k), wa, wb);
;     ...
;             BDOT(a0, 0) BDOT(a1, 1) BDOT(a2, 2) BDOT(a3, 3)
;     ...
;         }
;         a0 = wave_sum(a0); a1 = wave_sum(a1); a2 = wave_sum(a2); a3 = wave_sum(a3);
.Lp1b_row1:
	v_lshlrev_b32_e32 v12, 16, v48
	v_and_b32_e32 v13, 0xffff0000, v48
	v_lshlrev_b32_e32 v14, 16, v49
	v_and_b32_e32 v15, 0xffff0000, v49
	v_lshlrev_b32_e32 v16, 16, v50
	v_and_b32_e32 v17, 0xffff0000, v50
	v_lshlrev_b32_e32 v18, 16, v51
	v_and_b32_e32 v19, 0xffff0000, v51
	v_lshlrev_b32_e32 v20, 16, v52
	v_and_b32_e32 v21, 0xffff0000, v52
	v_lshlrev_b32_e32 v22, 16, v53
	v_and_b32_e32 v23, 0xffff0000, v53
	v_lshlrev_b32_e32 v24, 16, v54
	v_and_b32_e32 v25, 0xffff0000, v54
	v_lshlrev_b32_e32 v26, 16, v55
	v_and_b32_e32 v27, 0xffff0000, v55
	v_mul_f32_e32 v232, v12, v100
	v_mul_f32_e32 v233, v12, v116
	v_mul_f32_e32 v234, v12, v132
	v_mul_f32_e32 v235, v12, v148
	v_fmac_f32_e32 v232, v13, v101
	v_fmac_f32_e32 v233, v13, v117
	v_fmac_f32_e32 v234, v13, v133
	v_fmac_f32_e32 v235, v13, v149
	v_fmac_f32_e32 v232, v14, v102
	v_fmac_f32_e32 v233, v14, v118
	v_fmac_f32_e32 v234, v14, v134
	v_fmac_f32_e32 v235, v14, v150
	v_fmac_f32_e32 v232, v15, v103
	v_fmac_f32_e32 v233, v15, v119
	v_fmac_f32_e32 v234, v15, v135
	v_fmac_f32_e32 v235, v15, v151
	v_fmac_f32_e32 v232, v16, v104
	v_fmac_f32_e32 v233, v16, v120
	v_fmac_f32_e32 v234, v16, v136
	v_fmac_f32_e32 v235, v16, v152
	v_fmac_f32_e32 v232, v17, v105
	v_fmac_f32_e32 v233, v17, v121
	v_fmac_f32_e32 v234, v17, v137
	v_fmac_f32_e32 v235, v17, v153
	v_fmac_f32_e32 v232, v18, v106
	v_fmac_f32_e32 v233, v18, v122
	v_fmac_f32_e32 v234, v18, v138
	v_fmac_f32_e32 v235, v18, v154
	v_fmac_f32_e32 v232, v19, v107
	v_fmac_f32_e32 v233, v19, v123
	v_fmac_f32_e32 v234, v19, v139
	v_fmac_f32_e32 v235, v19, v155
	v_fmac_f32_e32 v232, v20, v108
	v_fmac_f32_e32 v233, v20, v124
	v_fmac_f32_e32 v234, v20, v140
	v_fmac_f32_e32 v235, v20, v156
	v_fmac_f32_e32 v232, v21, v109
	v_fmac_f32_e32 v233, v21, v125
	v_fmac_f32_e32 v234, v21, v141
	v_fmac_f32_e32 v235, v21, v157
	v_fmac_f32_e32 v232, v22, v110
	v_fmac_f32_e32 v233, v22, v126
	v_fmac_f32_e32 v234, v22, v142
	v_fmac_f32_e32 v235, v22, v158
	v_fmac_f32_e32 v232, v23, v111
	v_fmac_f32_e32 v233, v23, v127
	v_fmac_f32_e32 v234, v23, v143
	v_fmac_f32_e32 v235, v23, v159
	v_fmac_f32_e32 v232, v24, v112
	v_fmac_f32_e32 v233, v24, v128
	v_fmac_f32_e32 v234, v24, v144
	v_fmac_f32_e32 v235, v24, v160
	v_fmac_f32_e32 v232, v25, v113
	v_fmac_f32_e32 v233, v25, v129
	v_fmac_f32_e32 v234, v25, v145
	v_fmac_f32_e32 v235, v25, v161
	v_fmac_f32_e32 v232, v26, v114
	v_fmac_f32_e32 v233, v26, v130
	v_fmac_f32_e32 v234, v26, v146
	v_fmac_f32_e32 v235, v26, v162
	v_fmac_f32_e32 v232, v27, v115
	v_fmac_f32_e32 v233, v27, v131
	v_fmac_f32_e32 v234, v27, v147
	v_fmac_f32_e32 v235, v27, v163
	v_add_f32_dpp v232, v232, v232 quad_perm:[1,0,3,2] row_mask:0xf bank_mask:0xf
	v_add_f32_dpp v233, v233, v233 quad_perm:[1,0,3,2] row_mask:0xf bank_mask:0xf
	v_add_f32_dpp v234, v234, v234 quad_perm:[1,0,3,2] row_mask:0xf bank_mask:0xf
	v_add_f32_dpp v235, v235, v235 quad_perm:[1,0,3,2] row_mask:0xf bank_mask:0xf
	v_add_f32_dpp v232, v232, v232 quad_perm:[2,3,0,1] row_mask:0xf bank_mask:0xf
	v_add_f32_dpp v233, v233, v233 quad_perm:[2,3,0,1] row_mask:0xf bank_mask:0xf
	v_add_f32_dpp v234, v234, v234 quad_perm:[2,3,0,1] row_mask:0xf bank_mask:0xf
	v_add_f32_dpp v235, v235, v235 quad_perm:[2,3,0,1] row_mask:0xf bank_mask:0xf
	v_add_f32_dpp v232, v232, v232 row_half_mirror row_mask:0xf bank_mask:0xf
	v_add_f32_dpp v233, v233, v233 row_half_mirror row_mask:0xf bank_mask:0xf
	v_add_f32_dpp v234, v234, v234 row_half_mirror row_mask:0xf bank_mask:0xf
	v_add_f32_dpp v235, v235, v235 row_half_mirror row_mask:0xf bank_mask:0xf
	v_add_f32_dpp v232, v232, v232 row_mirror row_mask:0xf bank_mask:0xf
	v_add_f32_dpp v233, v233, v233 row_mirror row_mask:0xf bank_mask:0xf
	v_add_f32_dpp v234, v234, v234 row_mirror row_mask:0xf bank_mask:0xf
	v_add_f32_dpp v235, v235, v235 row_mirror row_mask:0xf bank_mask:0xf
	v_add_f32_dpp v232, v232, v232 row_bcast:15 row_mask:0xa bank_mask:0xf
	v_add_f32_dpp v233, v233, v233 row_bcast:15 row_mask:0xa bank_mask:0xf
	v_add_f32_dpp v234, v234, v234 row_bcast:15 row_mask:0xa bank_mask:0xf
	v_add_f32_dpp v235, v235, v235 row_bcast:15 row_mask:0xa bank_mask:0xf
	v_add_f32_dpp v232, v232, v232 row_bcast:31 row_mask:0xc bank_mask:0xf
	v_add_f32_dpp v233, v233, v233 row_bcast:31 row_mask:0xc bank_mask:0xf
	v_add_f32_dpp v234, v234, v234 row_bcast:31 row_mask:0xc bank_mask:0xf
	v_add_f32_dpp v235, v235, v235 row_bcast:31 row_mask:0xc bank_mask:0xf
	s_add_i32 s20, s20, -1
	s_cmp_eq_u32 s20, 0
	s_cbranch_scc1 .Lp1b_done
; __device__ __forceinline__ void p1_rows(const Args& A, int lane, int wave) {
;     ...
; #pragma unroll
;         for (int j = 0; j < 2; ++j) { const int k = 8 * lane + 512 * j; f32x4 wa, wb; pg8::unpack8(*(const u32x4*)(wrow + k), wa, wb);
;     ...
;             BDOT(a0, 0) BDOT(a1, 1) BDOT(a2, 2) BDOT(a3, 3)
;     ...
;         }
;         a0 = wave_sum(a0); a1 = wave_sum(a1); a2 = wave_sum(a2); a3 = wave_sum(a3);
.Lp1b_row2:
	v_lshlrev_b32_e32 v12, 16, v56
	v_and_b32_e32 v13, 0xffff0000, v56
	v_lshlrev_b32_e32 v14, 16, v57
	v_and_b32_e32 v15, 0xffff0000, v57
	v_lshlrev_b32_e32 v16, 16, v58
	v_and_b32_e32 v17, 0xffff0000, v58
	v_lshlrev_b32_e32 v18, 16, v59
	v_and_b32_e32 v19, 0xffff0000, v59
	v_lshlrev_b32_e32 v20, 16, v60
	v_and_b32_e32 v21, 0xffff0000, v60
	v_lshlrev_b32_e32 v22, 16, v61
	v_and_b32_e32 v23, 0xffff0000, v61
	v_lshlrev_b32_e32 v24, 16, v62
	v_and_b32_e32 v25, 0xffff0000, v62
	v_lshlrev_b32_e32 v26, 16, v63
	v_and_b32_e32 v27, 0xffff0000, v63
	v_mul_f32_e32 v236, v12, v100
	v_mul_f32_e32 v237, v12, v116
	v_mul_f32_e32 v238, v12, v132
	v_mul_f32_e32 v239, v12, v148
	v_fmac_f32_e32 v236, v13, v101
	v_fmac_f32_e32 v237, v13, v117
	v_fmac_f32_e32 v238, v13, v133
	v_fmac_f32_e32 v239, v13, v149
	v_fmac_f32_e32 v236, v14, v102
	v_fmac_f32_e32 v237, v14, v118
	v_fmac_f32_e32 v238, v14, v134
	v_fmac_f32_e32 v239, v14, v150
	v_fmac_f32_e32 v236, v15, v103
	v_fmac_f32_e32 v237, v15, v119
	v_fmac_f32_e32 v238, v15, v135
	v_fmac_f32_e32 v239, v15, v151
	v_fmac_f32_e32 v236, v16, v104
	v_fmac_f32_e32 v237, v16, v120
	v_fmac_f32_e32 v238, v16, v136
	v_fmac_f32_e32 v239, v16, v152
	v_fmac_f32_e32 v236, v17, v105
	v_fmac_f32_e32 v237, v17, v121
	v_fmac_f32_e32 v238, v17, v137
	v_fmac_f32_e32 v239, v17, v153
	v_fmac_f32_e32 v236, v18, v106
	v_fmac_f32_e32 v237, v18, v122
	v_fmac_f32_e32 v238, v18, v138
	v_fmac_f32_e32 v239, v18, v154
	v_fmac_f32_e32 v236, v19, v107
	v_fmac_f32_e32 v237, v19, v123
	v_fmac_f32_e32 v238, v19, v139
	v_fmac_f32_e32 v239, v19, v155
	v_fmac_f32_e32 v236, v20, v108
	v_fmac_f32_e32 v237, v20, v124
	v_fmac_f32_e32 v238, v20, v140
	v_fmac_f32_e32 v239, v20, v156
	v_fmac_f32_e32 v236, v21, v109
	v_fmac_f32_e32 v237, v21, v125
	v_fmac_f32_e32 v238, v21, v141
	v_fmac_f32_e32 v239, v21, v157
	v_fmac_f32_e32 v236, v22, v110
	v_fmac_f32_e32 v237, v22, v126
	v_fmac_f32_e32 v238, v22, v142
	v_fmac_f32_e32 v239, v22, v158
	v_fmac_f32_e32 v236, v23, v111
	v_fmac_f32_e32 v237, v23, v127
	v_fmac_f32_e32 v238, v23, v143
	v_fmac_f32_e32 v239, v23, v159
	v_fmac_f32_e32 v236, v24, v112
	v_fmac_f32_e32 v237, v24, v128
	v_fmac_f32_e32 v238, v24, v144
	v_fmac_f32_e32 v239, v24, v160
	v_fmac_f32_e32 v236, v25, v113
	v_fmac_f32_e32 v237, v25, v129
	v_fmac_f32_e32 v238, v25, v145
	v_fmac_f32_e32 v239, v25, v161
	v_fmac_f32_e32 v236, v26, v114
	v_fmac_f32_e32 v237, v26, v130
	v_fmac_f32_e32 v238, v26, v146
	v_fmac_f32_e32 v239, v26, v162
	v_fmac_f32_e32 v236, v27, v115
	v_fmac_f32_e32 v237, v27, v131
	v_fmac_f32_e32 v238, v27, v147
	v_fmac_f32_e32 v239, v27, v163
	v_add_f32_dpp v236, v236, v236 quad_perm:[1,0,3,2] row_mask:0xf bank_mask:0xf
	v_add_f32_dpp v237, v237, v237 quad_perm:[1,0,3,2] row_mask:0xf bank_mask:0xf
	v_add_f32_dpp v238, v238, v238 quad_perm:[1,0,3,2] row_mask:0xf bank_mask:0xf
	v_add_f32_dpp v239, v239, v239 quad_perm:[1,0,3,2] row_mask:0xf bank_mask:0xf
	v_add_f32_dpp v236, v236, v236 quad_perm:[2,3,0,1] row_mask:0xf bank_mask:0xf
	v_add_f32_dpp v237, v237, v237 quad_perm:[2,3,0,1] row_mask:0xf bank_mask:0xf
	v_add_f32_dpp v238, v238, v238 quad_perm:[2,3,0,1] row_mask:0xf bank_mask:0xf
	v_add_f32_dpp v239, v239, v239 quad_perm:[2,3,0,1] row_mask:0xf bank_mask:0xf
	v_add_f32_dpp v236, v236, v236 row_half_mirror row_mask:0xf bank_mask:0xf
	v_add_f32_dpp v237, v237, v237 row_half_mirror row_mask:0xf bank_mask:0xf
	v_add_f32_dpp v238, v238, v238 row_half_mirror row_mask:0xf bank_mask:0xf
	v_add_f32_dpp v239, v239, v239 row_half_mirror row_mask:0xf bank_mask:0xf
	v_add_f32_dpp v236, v236, v236 row_mirror row_mask:0xf bank_mask:0xf
	v_add_f32_dpp v237, v237, v237 row_mirror row_mask:0xf bank_mask:0xf
	v_add_f32_dpp v238, v238, v238 row_mirror row_mask:0xf bank_mask:0xf
	v_add_f32_dpp v239, v239, v239 row_mirror row_mask:0xf bank_mask:0xf
	v_add_f32_dpp v236, v236, v236 row_bcast:15 row_mask:0xa bank_mask:0xf
	v_add_f32_dpp v237, v237, v237 row_bcast:15 row_mask:0xa bank_mask:0xf
	v_add_f32_dpp v238, v238, v238 row_bcast:15 row_mask:0xa bank_mask:0xf
	v_add_f32_dpp v239, v239, v239 row_bcast:15 row_mask:0xa bank_mask:0xf
	v_add_f32_dpp v236, v236, v236 row_bcast:31 row_mask:0xc bank_mask:0xf
	v_add_f32_dpp v237, v237, v237 row_bcast:31 row_mask:0xc bank_mask:0xf
	v_add_f32_dpp v238, v238, v238 row_bcast:31 row_mask:0xc bank_mask:0xf
	v_add_f32_dpp v239, v239, v239 row_bcast:31 row_mask:0xc bank_mask:0xf
	s_add_i32 s20, s20, -1
	s_cmp_eq_u32 s20, 0
	s_cbranch_scc1 .Lp1b_done
; __device__ __forceinline__ void p1_rows(const Args& A, int lane, int wave) {
;     ...
;         const bool second = it >= DIN; const int dr = second ? it - DIN : it;
;         const bf16_t* wrow = (const bf16_t*)(ws + (second ? WS_W2GU : WS_WIN)) + (size_t)dr * DM;
;         const float* sh = mods + (second ? MOD_SH3 : MOD_SH2) * DM;
;         float a0 = 0.f, a1 = 0.f, a2 = 0.f, a3 = 0.f;
; #pragma unroll
;         for (int j = 0; j < 2; ++j) { const int k = 8 * lane + 512 * j; f32x4 wa, wb; pg8::unpack8(*(const u32x4*)(wrow + k), wa, wb);
;     ...
;             BDOT(a0, 0) BDOT(a1, 1) BDOT(a2, 2) BDOT(a3, 3)
;     ...
;         }
;         a0 = wave_sum(a0); a1 = wave_sum(a1); a2 = wave_sum(a2); a3 = wave_sum(a3);
.Lp1b_row3:
	s_add_i32 s0, s6, s8
	s_add_i32 s0, s0, s8
	s_add_i32 s0, s0, s8
	s_cmpk_gt_i32 s0, 0x19ff
	s_cbranch_scc1 .Lp1b_r3b
	v_lshlrev_b32_e32 v12, 16, v64
	v_and_b32_e32 v13, 0xffff0000, v64
	v_lshlrev_b32_e32 v14, 16, v65
	v_and_b32_e32 v15, 0xffff0000, v65
	v_lshlrev_b32_e32 v16, 16, v66
	v_and_b32_e32 v17, 0xffff0000, v66
	v_lshlrev_b32_e32 v18, 16, v67
	v_and_b32_e32 v19, 0xffff0000, v67
	v_lshlrev_b32_e32 v20, 16, v68
	v_and_b32_e32 v21, 0xffff0000, v68
	v_lshlrev_b32_e32 v22, 16, v69
	v_and_b32_e32 v23, 0xffff0000, v69
	v_lshlrev_b32_e32 v24, 16, v70
	v_and_b32_e32 v25, 0xffff0000, v70
	v_lshlrev_b32_e32 v26, 16, v71
	v_and_b32_e32 v27, 0xffff0000, v71
	v_mul_f32_e32 v240, v12, v100
	v_mul_f32_e32 v241, v12, v116
	v_mul_f32_e32 v242, v12, v132
	v_mul_f32_e32 v243, v12, v148
	v_fmac_f32_e32 v240, v13, v101
	v_fmac_f32_e32 v241, v13, v117
	v_fmac_f32_e32 v242, v13, v133
	v_fmac_f32_e32 v243, v13, v149
	v_fmac_f32_e32 v240, v14, v102
	v_fmac_f32_e32 v241, v14, v118
	v_fmac_f32_e32 v242, v14, v134
	v_fmac_f32_e32 v243, v14, v150
	v_fmac_f32_e32 v240, v15, v103
	v_fmac_f32_e32 v241, v15, v119
	v_fmac_f32_e32 v242, v15, v135
	v_fmac_f32_e32 v243, v15, v151
	v_fmac_f32_e32 v240, v16, v104
	v_fmac_f32_e32 v241, v16, v120
	v_fmac_f32_e32 v242, v16, v136
	v_fmac_f32_e32 v243, v16, v152
	v_fmac_f32_e32 v240, v17, v105
	v_fmac_f32_e32 v241, v17, v121
	v_fmac_f32_e32 v242, v17, v137
	v_fmac_f32_e32 v243, v17, v153
	v_fmac_f32_e32 v240, v18, v106
	v_fmac_f32_e32 v241, v18, v122
	v_fmac_f32_e32 v242, v18, v138
	v_fmac_f32_e32 v243, v18, v154
	v_fmac_f32_e32 v240, v19, v107
	v_fmac_f32_e32 v241, v19, v123
	v_fmac_f32_e32 v242, v19, v139
	v_fmac_f32_e32 v243, v19, v155
	v_fmac_f32_e32 v240, v20, v108
	v_fmac_f32_e32 v241, v20, v124
	v_fmac_f32_e32 v242, v20, v140
	v_fmac_f32_e32 v243, v20, v156
	v_fmac_f32_e32 v240, v21, v109
	v_fmac_f32_e32 v241, v21, v125
	v_fmac_f32_e32 v242, v21, v141
	v_fmac_f32_e32 v243, v21, v157
	v_fmac_f32_e32 v240, v22, v110
	v_fmac_f32_e32 v241, v22, v126
	v_fmac_f32_e32 v242, v22, v142
	v_fmac_f32_e32 v243, v22, v158
	v_fmac_f32_e32 v240, v23, v111
	v_fmac_f32_e32 v241, v23, v127
	v_fmac_f32_e32 v242, v23, v143
	v_fmac_f32_e32 v243, v23, v159
	v_fmac_f32_e32 v240, v24, v112
	v_fmac_f32_e32 v241, v24, v128
	v_fmac_f32_e32 v242, v24, v144
	v_fmac_f32_e32 v243, v24, v160
	v_fmac_f32_e32 v240, v25, v113
	v_fmac_f32_e32 v241, v25, v129
	v_fmac_f32_e32 v242, v25, v145
	v_fmac_f32_e32 v243, v25, v161
	v_fmac_f32_e32 v240, v26, v114
	v_fmac_f32_e32 v241, v26, v130
	v_fmac_f32_e32 v242, v26, v146
	v_fmac_f32_e32 v243, v26, v162
	v_fmac_f32_e32 v240, v27, v115
	v_fmac_f32_e32 v241, v27, v131
	v_fmac_f32_e32 v242, v27, v147
	v_fmac_f32_e32 v243, v27, v163
	v_add_f32_dpp v240, v240, v240 quad_perm:[1,0,3,2] row_mask:0xf bank_mask:0xf
	v_add_f32_dpp v241, v241, v241 quad_perm:[1,0,3,2] row_mask:0xf bank_mask:0xf
	v_add_f32_dpp v242, v242, v242 quad_perm:[1,0,3,2] row_mask:0xf bank_mask:0xf
	v_add_f32_dpp v243, v243, v243 quad_perm:[1,0,3,2] row_mask:0xf bank_mask:0xf
	v_add_f32_dpp v240, v240, v240 quad_perm:[2,3,0,1] row_mask:0xf bank_mask:0xf
	v_add_f32_dpp v241, v241, v241 quad_perm:[2,3,0,1] row_mask:0xf bank_mask:0xf
	v_add_f32_dpp v242, v242, v242 quad_perm:[2,3,0,1] row_mask:0xf bank_mask:0xf
	v_add_f32_dpp v243, v243, v243 quad_perm:[2,3,0,1] row_mask:0xf bank_mask:0xf
	v_add_f32_dpp v240, v240, v240 row_half_mirror row_mask:0xf bank_mask:0xf
	v_add_f32_dpp v241, v241, v241 row_half_mirror row_mask:0xf bank_mask:0xf
	v_add_f32_dpp v242, v242, v242 row_half_mirror row_mask:0xf bank_mask:0xf
	v_add_f32_dpp v243, v243, v243 row_half_mirror row_mask:0xf bank_mask:0xf
	v_add_f32_dpp v240, v240, v240 row_mirror row_mask:0xf bank_mask:0xf
	v_add_f32_dpp v241, v241, v241 row_mirror row_mask:0xf bank_mask:0xf
	v_add_f32_dpp v242, v242, v242 row_mirror row_mask:0xf bank_mask:0xf
	v_add_f32_dpp v243, v243, v243 row_mirror row_mask:0xf bank_mask:0xf
	v_add_f32_dpp v240, v240, v240 row_bcast:15 row_mask:0xa bank_mask:0xf
	v_add_f32_dpp v241, v241, v241 row_bcast:15 row_mask:0xa bank_mask:0xf
	v_add_f32_dpp v242, v242, v242 row_bcast:15 row_mask:0xa bank_mask:0xf
	v_add_f32_dpp v243, v243, v243 row_bcast:15 row_mask:0xa bank_mask:0xf
	v_add_f32_dpp v240, v240, v240 row_bcast:31 row_mask:0xc bank_mask:0xf
	v_add_f32_dpp v241, v241, v241 row_bcast:31 row_mask:0xc bank_mask:0xf
	v_add_f32_dpp v242, v242, v242 row_bcast:31 row_mask:0xc bank_mask:0xf
	v_add_f32_dpp v243, v243, v243 row_bcast:31 row_mask:0xc bank_mask:0xf
	s_branch .Lp1b_r3d
; __device__ __forceinline__ void p1_rows(const Args& A, int lane, int wave) {
;     ...
;         const bool second = it >= DIN; const int dr = second ? it - DIN : it;
;         const bf16_t* wrow = (const bf16_t*)(ws + (second ? WS_W2GU : WS_WIN)) + (size_t)dr * DM;
;         const float* sh = mods + (second ? MOD_SH3 : MOD_SH2) * DM;
;         float a0 = 0.f, a1 = 0.f, a2 = 0.f, a3 = 0.f;
; #pragma unroll
;         for (int j = 0; j < 2; ++j) { const int k = 8 * lane + 512 * j; f32x4 wa, wb; pg8::unpack8(*(const u32x4*)(wrow + k), wa, wb);
;     ...
;             BDOT(a0, 0) BDOT(a1, 1) BDOT(a2, 2) BDOT(a3, 3)
;     ...
;         }
;         a0 = wave_sum(a0); a1 = wave_sum(a1); a2 = wave_sum(a2); a3 = wave_sum(a3);
.Lp1b_r3b:
	v_lshlrev_b32_e32 v12, 16, v64
	v_and_b32_e32 v13, 0xffff0000, v64
	v_lshlrev_b32_e32 v14, 16, v65
	v_and_b32_e32 v15, 0xffff0000, v65
	v_lshlrev_b32_e32 v16, 16, v66
	v_and_b32_e32 v17, 0xffff0000, v66
	v_lshlrev_b32_e32 v18, 16, v67
	v_and_b32_e32 v19, 0xffff0000, v67
	v_lshlrev_b32_e32 v20, 16, v68
	v_and_b32_e32 v21, 0xffff0000, v68
	v_lshlrev_b32_e32 v22, 16, v69
	v_and_b32_e32 v23, 0xffff0000, v69
	v_lshlrev_b32_e32 v24, 16, v70
	v_and_b32_e32 v25, 0xffff0000, v70
	v_lshlrev_b32_e32 v26, 16, v71
	v_and_b32_e32 v27, 0xffff0000, v71
	v_mul_f32_e32 v240, v12, v164
	v_mul_f32_e32 v241, v12, v180
	v_mul_f32_e32 v242, v12, v196
	v_mul_f32_e32 v243, v12, v212
	v_fmac_f32_e32 v240, v13, v165
	v_fmac_f32_e32 v241, v13, v181
	v_fmac_f32_e32 v242, v13, v197
	v_fmac_f32_e32 v243, v13, v213
	v_fmac_f32_e32 v240, v14, v166
	v_fmac_f32_e32 v241, v14, v182
	v_fmac_f32_e32 v242, v14, v198
	v_fmac_f32_e32 v243, v14, v214
	v_fmac_f32_e32 v240, v15, v167
	v_fmac_f32_e32 v241, v15, v183
	v_fmac_f32_e32 v242, v15, v199
	v_fmac_f32_e32 v243, v15, v215
	v_fmac_f32_e32 v240, v16, v168
	v_fmac_f32_e32 v241, v16, v184
	v_fmac_f32_e32 v242, v16, v200
	v_fmac_f32_e32 v243, v16, v216
	v_fmac_f32_e32 v240, v17, v169
	v_fmac_f32_e32 v241, v17, v185
	v_fmac_f32_e32 v242, v17, v201
	v_fmac_f32_e32 v243, v17, v217
	v_fmac_f32_e32 v240, v18, v170
	v_fmac_f32_e32 v241, v18, v186
	v_fmac_f32_e32 v242, v18, v202
	v_fmac_f32_e32 v243, v18, v218
	v_fmac_f32_e32 v240, v19, v171
	v_fmac_f32_e32 v241, v19, v187
	v_fmac_f32_e32 v242, v19, v203
	v_fmac_f32_e32 v243, v19, v219
	v_fmac_f32_e32 v240, v20, v172
	v_fmac_f32_e32 v241, v20, v188
	v_fmac_f32_e32 v242, v20, v204
	v_fmac_f32_e32 v243, v20, v88
	v_fmac_f32_e32 v240, v21, v173
	v_fmac_f32_e32 v241, v21, v189
	v_fmac_f32_e32 v242, v21, v205
	v_fmac_f32_e32 v243, v21, v89
	v_fmac_f32_e32 v240, v22, v174
	v_fmac_f32_e32 v241, v22, v190
	v_fmac_f32_e32 v242, v22, v206
	v_fmac_f32_e32 v243, v22, v90
	v_fmac_f32_e32 v240, v23, v175
	v_fmac_f32_e32 v241, v23, v191
	v_fmac_f32_e32 v242, v23, v207
	v_fmac_f32_e32 v243, v23, v91
	v_fmac_f32_e32 v240, v24, v176
	v_fmac_f32_e32 v241, v24, v192
	v_fmac_f32_e32 v242, v24, v208
	v_fmac_f32_e32 v243, v24, v92
	v_fmac_f32_e32 v240, v25, v177
	v_fmac_f32_e32 v241, v25, v193
	v_fmac_f32_e32 v242, v25, v209
	v_fmac_f32_e32 v243, v25, v93
	v_fmac_f32_e32 v240, v26, v178
	v_fmac_f32_e32 v241, v26, v194
	v_fmac_f32_e32 v242, v26, v210
	v_fmac_f32_e32 v243, v26, v94
	v_fmac_f32_e32 v240, v27, v179
	v_fmac_f32_e32 v241, v27, v195
	v_fmac_f32_e32 v242, v27, v211
	v_fmac_f32_e32 v243, v27, v95
	v_add_f32_dpp v240, v240, v240 quad_perm:[1,0,3,2] row_mask:0xf bank_mask:0xf
	v_add_f32_dpp v241, v241, v241 quad_perm:[1,0,3,2] row_mask:0xf bank_mask:0xf
	v_add_f32_dpp v242, v242, v242 quad_perm:[1,0,3,2] row_mask:0xf bank_mask:0xf
	v_add_f32_dpp v243, v243, v243 quad_perm:[1,0,3,2] row_mask:0xf bank_mask:0xf
	v_add_f32_dpp v240, v240, v240 quad_perm:[2,3,0,1] row_mask:0xf bank_mask:0xf
	v_add_f32_dpp v241, v241, v241 quad_perm:[2,3,0,1] row_mask:0xf bank_mask:0xf
	v_add_f32_dpp v242, v242, v242 quad_perm:[2,3,0,1] row_mask:0xf bank_mask:0xf
	v_add_f32_dpp v243, v243, v243 quad_perm:[2,3,0,1] row_mask:0xf bank_mask:0xf
	v_add_f32_dpp v240, v240, v240 row_half_mirror row_mask:0xf bank_mask:0xf
	v_add_f32_dpp v241, v241, v241 row_half_mirror row_mask:0xf bank_mask:0xf
	v_add_f32_dpp v242, v242, v242 row_half_mirror row_mask:0xf bank_mask:0xf
	v_add_f32_dpp v243, v243, v243 row_half_mirror row_mask:0xf bank_mask:0xf
	v_add_f32_dpp v240, v240, v240 row_mirror row_mask:0xf bank_mask:0xf
	v_add_f32_dpp v241, v241, v241 row_mirror row_mask:0xf bank_mask:0xf
	v_add_f32_dpp v242, v242, v242 row_mirror row_mask:0xf bank_mask:0xf
	v_add_f32_dpp v243, v243, v243 row_mirror row_mask:0xf bank_mask:0xf
	v_add_f32_dpp v240, v240, v240 row_bcast:15 row_mask:0xa bank_mask:0xf
	v_add_f32_dpp v241, v241, v241 row_bcast:15 row_mask:0xa bank_mask:0xf
	v_add_f32_dpp v242, v242, v242 row_bcast:15 row_mask:0xa bank_mask:0xf
	v_add_f32_dpp v243, v243, v243 row_bcast:15 row_mask:0xa bank_mask:0xf
	v_add_f32_dpp v240, v240, v240 row_bcast:31 row_mask:0xc bank_mask:0xf
	v_add_f32_dpp v241, v241, v241 row_bcast:31 row_mask:0xc bank_mask:0xf
	v_add_f32_dpp v242, v242, v242 row_bcast:31 row_mask:0xc bank_mask:0xf
	v_add_f32_dpp v243, v243, v243 row_bcast:31 row_mask:0xc bank_mask:0xf
.Lp1b_r3d:
	s_add_i32 s20, s20, -1
	s_cmp_eq_u32 s20, 0
	s_cbranch_scc1 .Lp1b_done
; __device__ __forceinline__ void p1_rows(const Args& A, int lane, int wave) {
;     ...
; #pragma unroll
;         for (int j = 0; j < 2; ++j) { const int k = 8 * lane + 512 * j; f32x4 wa, wb; pg8::unpack8(*(const u32x4*)(wrow + k), wa, wb);
;     ...
;             BDOT(a0, 0) BDOT(a1, 1) BDOT(a2, 2) BDOT(a3, 3)
;     ...
;         }
;         a0 = wave_sum(a0); a1 = wave_sum(a1); a2 = wave_sum(a2); a3 = wave_sum(a3);
.Lp1b_row4:
	v_lshlrev_b32_e32 v12, 16, v72
	v_and_b32_e32 v13, 0xffff0000, v72
	v_lshlrev_b32_e32 v14, 16, v73
	v_and_b32_e32 v15, 0xffff0000, v73
	v_lshlrev_b32_e32 v16, 16, v74
	v_and_b32_e32 v17, 0xffff0000, v74
	v_lshlrev_b32_e32 v18, 16, v75
	v_and_b32_e32 v19, 0xffff0000, v75
	v_lshlrev_b32_e32 v20, 16, v76
	v_and_b32_e32 v21, 0xffff0000, v76
	v_lshlrev_b32_e32 v22, 16, v77
	v_and_b32_e32 v23, 0xffff0000, v77
	v_lshlrev_b32_e32 v24, 16, v78
	v_and_b32_e32 v25, 0xffff0000, v78
	v_lshlrev_b32_e32 v26, 16, v79
	v_and_b32_e32 v27, 0xffff0000, v79
	v_mul_f32_e32 v244, v12, v164
	v_mul_f32_e32 v245, v12, v180
	v_mul_f32_e32 v246, v12, v196
	v_mul_f32_e32 v247, v12, v212
	v_fmac_f32_e32 v244, v13, v165
	v_fmac_f32_e32 v245, v13, v181
	v_fmac_f32_e32 v246, v13, v197
	v_fmac_f32_e32 v247, v13, v213
	v_fmac_f32_e32 v244, v14, v166
	v_fmac_f32_e32 v245, v14, v182
	v_fmac_f32_e32 v246, v14, v198
	v_fmac_f32_e32 v247, v14, v214
	v_fmac_f32_e32 v244, v15, v167
	v_fmac_f32_e32 v245, v15, v183
	v_fmac_f32_e32 v246, v15, v199
	v_fmac_f32_e32 v247, v15, v215
	v_fmac_f32_e32 v244, v16, v168
	v_fmac_f32_e32 v245, v16, v184
	v_fmac_f32_e32 v246, v16, v200
	v_fmac_f32_e32 v247, v16, v216
	v_fmac_f32_e32 v244, v17, v169
	v_fmac_f32_e32 v245, v17, v185
	v_fmac_f32_e32 v246, v17, v201
	v_fmac_f32_e32 v247, v17, v217
	v_fmac_f32_e32 v244, v18, v170
	v_fmac_f32_e32 v245, v18, v186
	v_fmac_f32_e32 v246, v18, v202
	v_fmac_f32_e32 v247, v18, v218
	v_fmac_f32_e32 v244, v19, v171
	v_fmac_f32_e32 v245, v19, v187
	v_fmac_f32_e32 v246, v19, v203
	v_fmac_f32_e32 v247, v19, v219
	v_fmac_f32_e32 v244, v20, v172
	v_fmac_f32_e32 v245, v20, v188
	v_fmac_f32_e32 v246, v20, v204
	v_fmac_f32_e32 v247, v20, v88
	v_fmac_f32_e32 v244, v21, v173
	v_fmac_f32_e32 v245, v21, v189
	v_fmac_f32_e32 v246, v21, v205
	v_fmac_f32_e32 v247, v21, v89
	v_fmac_f32_e32 v244, v22, v174
	v_fmac_f32_e32 v245, v22, v190
	v_fmac_f32_e32 v246, v22, v206
	v_fmac_f32_e32 v247, v22, v90
	v_fmac_f32_e32 v244, v23, v175
	v_fmac_f32_e32 v245, v23, v191
	v_fmac_f32_e32 v246, v23, v207
	v_fmac_f32_e32 v247, v23, v91
	v_fmac_f32_e32 v244, v24, v176
	v_fmac_f32_e32 v245, v24, v192
	v_fmac_f32_e32 v246, v24, v208
	v_fmac_f32_e32 v247, v24, v92
	v_fmac_f32_e32 v244, v25, v177
	v_fmac_f32_e32 v245, v25, v193
	v_fmac_f32_e32 v246, v25, v209
	v_fmac_f32_e32 v247, v25, v93
	v_fmac_f32_e32 v244, v26, v178
	v_fmac_f32_e32 v245, v26, v194
	v_fmac_f32_e32 v246, v26, v210
	v_fmac_f32_e32 v247, v26, v94
	v_fmac_f32_e32 v244, v27, v179
	v_fmac_f32_e32 v245, v27, v195
	v_fmac_f32_e32 v246, v27, v211
	v_fmac_f32_e32 v247, v27, v95
	v_add_f32_dpp v244, v244, v244 quad_perm:[1,0,3,2] row_mask:0xf bank_mask:0xf
	v_add_f32_dpp v245, v245, v245 quad_perm:[1,0,3,2] row_mask:0xf bank_mask:0xf
	v_add_f32_dpp v246, v246, v246 quad_perm:[1,0,3,2] row_mask:0xf bank_mask:0xf
	v_add_f32_dpp v247, v247, v247 quad_perm:[1,0,3,2] row_mask:0xf bank_mask:0xf
	v_add_f32_dpp v244, v244, v244 quad_perm:[2,3,0,1] row_mask:0xf bank_mask:0xf
	v_add_f32_dpp v245, v245, v245 quad_perm:[2,3,0,1] row_mask:0xf bank_mask:0xf
	v_add_f32_dpp v246, v246, v246 quad_perm:[2,3,0,1] row_mask:0xf bank_mask:0xf
	v_add_f32_dpp v247, v247, v247 quad_perm:[2,3,0,1] row_mask:0xf bank_mask:0xf
	v_add_f32_dpp v244, v244, v244 row_half_mirror row_mask:0xf bank_mask:0xf
	v_add_f32_dpp v245, v245, v245 row_half_mirror row_mask:0xf bank_mask:0xf
	v_add_f32_dpp v246, v246, v246 row_half_mirror row_mask:0xf bank_mask:0xf
	v_add_f32_dpp v247, v247, v247 row_half_mirror row_mask:0xf bank_mask:0xf
	v_add_f32_dpp v244, v244, v244 row_mirror row_mask:0xf bank_mask:0xf
	v_add_f32_dpp v245, v245, v245 row_mirror row_mask:0xf bank_mask:0xf
	v_add_f32_dpp v246, v246, v246 row_mirror row_mask:0xf bank_mask:0xf
	v_add_f32_dpp v247, v247, v247 row_mirror row_mask:0xf bank_mask:0xf
	v_add_f32_dpp v244, v244, v244 row_bcast:15 row_mask:0xa bank_mask:0xf
	v_add_f32_dpp v245, v245, v245 row_bcast:15 row_mask:0xa bank_mask:0xf
	v_add_f32_dpp v246, v246, v246 row_bcast:15 row_mask:0xa bank_mask:0xf
	v_add_f32_dpp v247, v247, v247 row_bcast:15 row_mask:0xa bank_mask:0xf
	v_add_f32_dpp v244, v244, v244 row_bcast:31 row_mask:0xc bank_mask:0xf
	v_add_f32_dpp v245, v245, v245 row_bcast:31 row_mask:0xc bank_mask:0xf
	v_add_f32_dpp v246, v246, v246 row_bcast:31 row_mask:0xc bank_mask:0xf
	v_add_f32_dpp v247, v247, v247 row_bcast:31 row_mask:0xc bank_mask:0xf
	s_add_i32 s20, s20, -1
	s_cmp_eq_u32 s20, 0
	s_cbranch_scc1 .Lp1b_done
; __device__ __forceinline__ void p1_rows(const Args& A, int lane, int wave) {
;     ...
; #pragma unroll
;         for (int j = 0; j < 2; ++j) { const int k = 8 * lane + 512 * j; f32x4 wa, wb; pg8::unpack8(*(const u32x4*)(wrow + k), wa, wb);
;     ...
;             BDOT(a0, 0) BDOT(a1, 1) BDOT(a2, 2) BDOT(a3, 3)
;     ...
;         }
;         a0 = wave_sum(a0); a1 = wave_sum(a1); a2 = wave_sum(a2); a3 = wave_sum(a3);
.Lp1b_row5:
	v_lshlrev_b32_e32 v12, 16, v80
	v_and_b32_e32 v13, 0xffff0000, v80
	v_lshlrev_b32_e32 v14, 16, v81
	v_and_b32_e32 v15, 0xffff0000, v81
	v_lshlrev_b32_e32 v16, 16, v82
	v_and_b32_e32 v17, 0xffff0000, v82
	v_lshlrev_b32_e32 v18, 16, v83
	v_and_b32_e32 v19, 0xffff0000, v83
	v_lshlrev_b32_e32 v20, 16, v84
	v_and_b32_e32 v21, 0xffff0000, v84
	v_lshlrev_b32_e32 v22, 16, v85
	v_and_b32_e32 v23, 0xffff0000, v85
	v_lshlrev_b32_e32 v24, 16, v86
	v_and_b32_e32 v25, 0xffff0000, v86
	v_lshlrev_b32_e32 v26, 16, v87
	v_and_b32_e32 v27, 0xffff0000, v87
	v_mul_f32_e32 v248, v12, v164
	v_mul_f32_e32 v249, v12, v180
	v_mul_f32_e32 v250, v12, v196
	v_mul_f32_e32 v251, v12, v212
	v_fmac_f32_e32 v248, v13, v165
	v_fmac_f32_e32 v249, v13, v181
	v_fmac_f32_e32 v250, v13, v197
	v_fmac_f32_e32 v251, v13, v213
	v_fmac_f32_e32 v248, v14, v166
	v_fmac_f32_e32 v249, v14, v182
	v_fmac_f32_e32 v250, v14, v198
	v_fmac_f32_e32 v251, v14, v214
	v_fmac_f32_e32 v248, v15, v167
	v_fmac_f32_e32 v249, v15, v183
	v_fmac_f32_e32 v250, v15, v199
	v_fmac_f32_e32 v251, v15, v215
	v_fmac_f32_e32 v248, v16, v168
	v_fmac_f32_e32 v249, v16, v184
	v_fmac_f32_e32 v250, v16, v200
	v_fmac_f32_e32 v251, v16, v216
	v_fmac_f32_e32 v248, v17, v169
	v_fmac_f32_e32 v249, v17, v185
	v_fmac_f32_e32 v250, v17, v201
	v_fmac_f32_e32 v251, v17, v217
	v_fmac_f32_e32 v248, v18, v170
	v_fmac_f32_e32 v249, v18, v186
	v_fmac_f32_e32 v250, v18, v202
	v_fmac_f32_e32 v251, v18, v218
	v_fmac_f32_e32 v248, v19, v171
	v_fmac_f32_e32 v249, v19, v187
	v_fmac_f32_e32 v250, v19, v203
	v_fmac_f32_e32 v251, v19, v219
	v_fmac_f32_e32 v248, v20, v172
	v_fmac_f32_e32 v249, v20, v188
	v_fmac_f32_e32 v250, v20, v204
	v_fmac_f32_e32 v251, v20, v88
	v_fmac_f32_e32 v248, v21, v173
	v_fmac_f32_e32 v249, v21, v189
	v_fmac_f32_e32 v250, v21, v205
	v_fmac_f32_e32 v251, v21, v89
	v_fmac_f32_e32 v248, v22, v174
	v_fmac_f32_e32 v249, v22, v190
	v_fmac_f32_e32 v250, v22, v206
	v_fmac_f32_e32 v251, v22, v90
	v_fmac_f32_e32 v248, v23, v175
	v_fmac_f32_e32 v249, v23, v191
	v_fmac_f32_e32 v250, v23, v207
	v_fmac_f32_e32 v251, v23, v91
	v_fmac_f32_e32 v248, v24, v176
	v_fmac_f32_e32 v249, v24, v192
	v_fmac_f32_e32 v250, v24, v208
	v_fmac_f32_e32 v251, v24, v92
	v_fmac_f32_e32 v248, v25, v177
	v_fmac_f32_e32 v249, v25, v193
	v_fmac_f32_e32 v250, v25, v209
	v_fmac_f32_e32 v251, v25, v93
	v_fmac_f32_e32 v248, v26, v178
	v_fmac_f32_e32 v249, v26, v194
	v_fmac_f32_e32 v250, v26, v210
	v_fmac_f32_e32 v251, v26, v94
	v_fmac_f32_e32 v248, v27, v179
	v_fmac_f32_e32 v249, v27, v195
	v_fmac_f32_e32 v250, v27, v211
	v_fmac_f32_e32 v251, v27, v95
	v_add_f32_dpp v248, v248, v248 quad_perm:[1,0,3,2] row_mask:0xf bank_mask:0xf
	v_add_f32_dpp v249, v249, v249 quad_perm:[1,0,3,2] row_mask:0xf bank_mask:0xf
	v_add_f32_dpp v250, v250, v250 quad_perm:[1,0,3,2] row_mask:0xf bank_mask:0xf
	v_add_f32_dpp v251, v251, v251 quad_perm:[1,0,3,2] row_mask:0xf bank_mask:0xf
	v_add_f32_dpp v248, v248, v248 quad_perm:[2,3,0,1] row_mask:0xf bank_mask:0xf
	v_add_f32_dpp v249, v249, v249 quad_perm:[2,3,0,1] row_mask:0xf bank_mask:0xf
	v_add_f32_dpp v250, v250, v250 quad_perm:[2,3,0,1] row_mask:0xf bank_mask:0xf
	v_add_f32_dpp v251, v251, v251 quad_perm:[2,3,0,1] row_mask:0xf bank_mask:0xf
	v_add_f32_dpp v248, v248, v248 row_half_mirror row_mask:0xf bank_mask:0xf
	v_add_f32_dpp v249, v249, v249 row_half_mirror row_mask:0xf bank_mask:0xf
	v_add_f32_dpp v250, v250, v250 row_half_mirror row_mask:0xf bank_mask:0xf
	v_add_f32_dpp v251, v251, v251 row_half_mirror row_mask:0xf bank_mask:0xf
	v_add_f32_dpp v248, v248, v248 row_mirror row_mask:0xf bank_mask:0xf
	v_add_f32_dpp v249, v249, v249 row_mirror row_mask:0xf bank_mask:0xf
	v_add_f32_dpp v250, v250, v250 row_mirror row_mask:0xf bank_mask:0xf
	v_add_f32_dpp v251, v251, v251 row_mirror row_mask:0xf bank_mask:0xf
	v_add_f32_dpp v248, v248, v248 row_bcast:15 row_mask:0xa bank_mask:0xf
	v_add_f32_dpp v249, v249, v249 row_bcast:15 row_mask:0xa bank_mask:0xf
	v_add_f32_dpp v250, v250, v250 row_bcast:15 row_mask:0xa bank_mask:0xf
	v_add_f32_dpp v251, v251, v251 row_bcast:15 row_mask:0xa bank_mask:0xf
	v_add_f32_dpp v248, v248, v248 row_bcast:31 row_mask:0xc bank_mask:0xf
	v_add_f32_dpp v249, v249, v249 row_bcast:31 row_mask:0xc bank_mask:0xf
	v_add_f32_dpp v250, v250, v250 row_bcast:31 row_mask:0xc bank_mask:0xf
	v_add_f32_dpp v251, v251, v251 row_bcast:31 row_mask:0xc bank_mask:0xf
	s_add_i32 s20, s20, -1
	s_cmp_eq_u32 s20, 0
	s_cbranch_scc1 .Lp1b_done
	s_branch .Lp1b_row0
; __device__ __forceinline__ void p1_rows(const Args& A, int lane, int wave) {
;     ...
;         if (lane == 0) { float* bo = (float*)(ws + (second ? WS_BIAS3 : WS_BIAS2)); const int N = second ? NGU : DIN;
;             bo[dr] = a0; bo[N + dr] = a1; bo[2 * N + dr] = a2; bo[3 * N + dr] = a3; }
.Lp1b_done:
	v_mov_b32_e32 v7, 0
	s_mov_b32 exec_lo, 0
	s_mov_b32 exec_hi, 0x80000000
	s_mov_b32 s14, 0x60000
	s_mov_b32 s15, 0x40000
	s_movk_i32 s18, 0x5800
	s_movk_i32 s19, 0x6800
	s_mov_b32 s0, s6
	s_add_i32 s9, s0, 0xffffe600
	s_cmpk_gt_i32 s0, 0x19ff
	s_cselect_b32 s9, s9, s0
	s_cselect_b32 s1, s14, s15
	s_cselect_b32 s10, s18, s19
	s_lshl_b32 s9, s9, 2
	s_add_u32 s12, s4, s1
	s_addc_u32 s13, s5, 0
	s_add_u32 s12, s12, s9
	s_addc_u32 s13, s13, 0
	s_lshl_b32 s11, s10, 1
	v_mov_b32_e32 v8, s10
	s_add_i32 s10, s11, s10
	v_mov_b32_e32 v9, s11
	v_mov_b32_e32 v10, s10
	global_store_dword v7, v228, s[12:13]
	global_store_dword v8, v229, s[12:13]
	global_store_dword v9, v230, s[12:13]
	global_store_dword v10, v231, s[12:13]
	s_add_i32 s0, s0, s8
	s_add_i32 s9, s0, 0xffffe600
	s_cmpk_gt_i32 s0, 0x19ff
	s_cselect_b32 s9, s9, s0
	s_cselect_b32 s1, s14, s15
	s_cselect_b32 s10, s18, s19
	s_lshl_b32 s9, s9, 2
	s_add_u32 s12, s4, s1
	s_addc_u32 s13, s5, 0
	s_add_u32 s12, s12, s9
	s_addc_u32 s13, s13, 0
	s_lshl_b32 s11, s10, 1
	v_mov_b32_e32 v8, s10
	s_add_i32 s10, s11, s10
	v_mov_b32_e32 v9, s11
	v_mov_b32_e32 v10, s10
	global_store_dword v7, v232, s[12:13]
	global_store_dword v8, v233, s[12:13]
	global_store_dword v9, v234, s[12:13]
	global_store_dword v10, v235, s[12:13]
	s_add_i32 s0, s0, s8
	s_add_i32 s9, s0, 0xffffe600
	s_cmpk_gt_i32 s0, 0x19ff
	s_cselect_b32 s9, s9, s0
	s_cselect_b32 s1, s14, s15
	s_cselect_b32 s10, s18, s19
	s_lshl_b32 s9, s9, 2
	s_add_u32 s12, s4, s1
	s_addc_u32 s13, s5, 0
	s_add_u32 s12, s12, s9
	s_addc_u32 s13, s13, 0
	s_lshl_b32 s11, s10, 1
	v_mov_b32_e32 v8, s10
	s_add_i32 s10, s11, s10
	v_mov_b32_e32 v9, s11
	v_mov_b32_e32 v10, s10
	global_store_dword v7, v236, s[12:13]
	global_store_dword v8, v237, s[12:13]
	global_store_dword v9, v238, s[12:13]
	global_store_dword v10, v239, s[12:13]
	s_add_i32 s0, s0, s8
	s_add_i32 s9, s0, 0xffffe600
	s_cmpk_gt_i32 s0, 0x19ff
	s_cselect_b32 s9, s9, s0
	s_cselect_b32 s1, s14, s15
	s_cselect_b32 s10, s18, s19
	s_lshl_b32 s9, s9, 2
	s_add_u32 s12, s4, s1
	s_addc_u32 s13, s5, 0
	s_add_u32 s12, s12, s9
	s_addc_u32 s13, s13, 0
	s_lshl_b32 s11, s10, 1
	v_mov_b32_e32 v8, s10
	s_add_i32 s10, s11, s10
	v_mov_b32_e32 v9, s11
	v_mov_b32_e32 v10, s10
	global_store_dword v7, v240, s[12:13]
	global_store_dword v8, v241, s[12:13]
	global_store_dword v9, v242, s[12:13]
	global_store_dword v10, v243, s[12:13]
	s_add_i32 s0, s0, s8
	s_add_i32 s9, s0, 0xffffe600
	s_cmpk_gt_i32 s0, 0x19ff
	s_cselect_b32 s9, s9, s0
	s_cselect_b32 s1, s14, s15
	s_cselect_b32 s10, s18, s19
	s_lshl_b32 s9, s9, 2
	s_add_u32 s12, s4, s1
	s_addc_u32 s13, s5, 0
	s_add_u32 s12, s12, s9
	s_addc_u32 s13, s13, 0
	s_lshl_b32 s11, s10, 1
	v_mov_b32_e32 v8, s10
	s_add_i32 s10, s11, s10
	v_mov_b32_e32 v9, s11
	v_mov_b32_e32 v10, s10
	global_store_dword v7, v244, s[12:13]
	global_store_dword v8, v245, s[12:13]
	global_store_dword v9, v246, s[12:13]
	global_store_dword v10, v247, s[12:13]
	s_add_i32 s0, s0, s8
	s_add_i32 s9, s0, 0xffffe600
	s_cmpk_gt_i32 s0, 0x19ff
	s_cselect_b32 s9, s9, s0
	s_cselect_b32 s1, s14, s15
	s_cselect_b32 s10, s18, s19
	s_lshl_b32 s9, s9, 2
	s_add_u32 s12, s4, s1
	s_addc_u32 s13, s5, 0
	s_add_u32 s12, s12, s9
	s_addc_u32 s13, s13, 0
	s_lshl_b32 s11, s10, 1
	v_mov_b32_e32 v8, s10
	s_add_i32 s10, s11, s10
	v_mov_b32_e32 v9, s11
	v_mov_b32_e32 v10, s10
	global_store_dword v7, v248, s[12:13]
	global_store_dword v8, v249, s[12:13]
	global_store_dword v9, v250, s[12:13]
	global_store_dword v10, v251, s[12:13]
	s_mov_b64 exec, -1
